# pool-GEMM epilogue: 16 a_gate loads issued up-front with counted waits, multiply in place then convert+store (on top of v8)
# baseline (speedup 1.0000x reference)
; __device__ __forceinline__ float bflo(unsigned w) { return __uint_as_float(w << 16); }
; __device__ __forceinline__ float bfhi(unsigned w) { return __uint_as_float(w & 0xffff0000u); }
; #define PG8_BAR __builtin_amdgcn_s_barrier()
; template <bool ALIGN_EPI, bool SP2, class Epi, class Sched>
; __device__ __forceinline__ void gemm_phase(LAS unsigned char* lds, const Gemm g, const Sched& S, const Epi& E) {
;     ...
;         if constexpr (ALIGN_EPI) { if (wr == 0) PG8_BAR; }
;     __device__ __forceinline__ void operator()(f32x4 (&acc)[2][2][4][2], const Unit& u, int wr, int wc, int fr, int fq) const {
;         const int g = u.pm >> 6; const int row0 = (u.pm & 63) * BM + wr * 64 + fr, col0 = g * 256 + wc * 32 + 8 * fq;
; #pragma unroll
;         for (int ai = 0; ai < 2; ++ai)
; #pragma unroll
;             for (int m = 0; m < 4; ++m) { const size_t row = (size_t)(row0 + ai * HALF + m * 16);
; #pragma unroll
;                 for (int bj = 0; bj < 2; ++bj) { const int col = col0 + bj * HALF;
;                     const u32x4 gt = *(const u32x4*)(HM + row * HMW + C_AGATE + col);
;                     const f32x4 v0 = acc[ai][bj][m][0], v1 = acc[ai][bj][m][1];
;                     u32x4 w; w.x = pk2(v0[0] * bflo(gt.x), v0[1] * bfhi(gt.x)); w.y = pk2(v0[2] * bflo(gt.y), v0[3] * bfhi(gt.y));
;                     w.z = pk2(v1[0] * bflo(gt.z), v1[1] * bfhi(gt.z)); w.w = pk2(v1[2] * bflo(gt.w), v1[3] * bfhi(gt.w));
;                     *(u32x4*)(YA + row * 1024 + col) = w; } }
;     }
.LBB0_621:
	s_lshl_b32 s24, s70, 8
	s_and_b32 s24, s24, 0x3f00
	v_add_u32_e32 v152, s24, v154
	s_lshl_b32 s24, s70, 2
	s_and_b32 s24, s24, 0xffffff00
	v_or_b32_e32 v153, s24, v156
	v_lshlrev_b32_e32 v153, 1, v153
	v_mul_lo_u32 v234, v152, s50
	v_add_u32_e32 v234, v234, v153
	global_load_dwordx4 v[148:151], v234, s[36:37] offset:2048
	global_load_dwordx4 v[158:161], v234, s[36:37] offset:2304
	v_add_u32_e32 v235, 0x42000, v234
	global_load_dwordx4 v[162:165], v235, s[36:37] offset:2048
	global_load_dwordx4 v[174:177], v235, s[36:37] offset:2304
	v_add_u32_e32 v235, 0x84000, v234
	global_load_dwordx4 v[178:181], v235, s[36:37] offset:2048
	global_load_dwordx4 v[182:185], v235, s[36:37] offset:2304
	v_add_u32_e32 v235, 0xc6000, v234
	global_load_dwordx4 v[186:189], v235, s[36:37] offset:2048
	global_load_dwordx4 v[190:193], v235, s[36:37] offset:2304
	v_add_u32_e32 v235, 0x210000, v234
	global_load_dwordx4 v[194:197], v235, s[36:37] offset:2048
	global_load_dwordx4 v[198:201], v235, s[36:37] offset:2304
	v_add_u32_e32 v235, 0x252000, v234
	global_load_dwordx4 v[202:205], v235, s[36:37] offset:2048
	global_load_dwordx4 v[206:209], v235, s[36:37] offset:2304
	v_add_u32_e32 v235, 0x294000, v234
	global_load_dwordx4 v[210:213], v235, s[36:37] offset:2048
	global_load_dwordx4 v[214:217], v235, s[36:37] offset:2304
	v_add_u32_e32 v235, 0x2d6000, v234
	global_load_dwordx4 v[218:221], v235, s[36:37] offset:2048
	global_load_dwordx4 v[222:225], v235, s[36:37] offset:2304
	s_and_b64 vcc, exec, s[44:45]
	s_cbranch_vccz .LBB0_623
	s_barrier
.LBB0_623:
	s_mov_b64 s[86:87], -1
	s_waitcnt vmcnt(15)
	v_lshlrev_b32_e32 v226, 16, v148
	v_and_b32_e32 v227, 0xffff0000, v148
	v_lshlrev_b32_e32 v228, 16, v149
	v_and_b32_e32 v229, 0xffff0000, v149
	v_lshlrev_b32_e32 v230, 16, v150
	v_and_b32_e32 v231, 0xffff0000, v150
	v_lshlrev_b32_e32 v232, 16, v151
	v_and_b32_e32 v233, 0xffff0000, v151
	v_mul_f32_e32 v126, v126, v226
	v_mul_f32_e32 v127, v127, v227
	v_mul_f32_e32 v128, v128, v228
	v_mul_f32_e32 v129, v129, v229
	v_mul_f32_e32 v122, v122, v230
	v_mul_f32_e32 v123, v123, v231
	v_mul_f32_e32 v124, v124, v232
	v_mul_f32_e32 v125, v125, v233
	s_waitcnt vmcnt(14)
	v_lshlrev_b32_e32 v226, 16, v158
	v_and_b32_e32 v227, 0xffff0000, v158
	v_lshlrev_b32_e32 v228, 16, v159
	v_and_b32_e32 v229, 0xffff0000, v159
	v_lshlrev_b32_e32 v230, 16, v160
	v_and_b32_e32 v231, 0xffff0000, v160
	v_lshlrev_b32_e32 v232, 16, v161
	v_and_b32_e32 v233, 0xffff0000, v161
	v_mul_f32_e32 v118, v118, v226
	v_mul_f32_e32 v119, v119, v227
	v_mul_f32_e32 v120, v120, v228
	v_mul_f32_e32 v121, v121, v229
	v_mul_f32_e32 v114, v114, v230
	v_mul_f32_e32 v115, v115, v231
	v_mul_f32_e32 v116, v116, v232
	v_mul_f32_e32 v117, v117, v233
	s_waitcnt vmcnt(13)
	v_lshlrev_b32_e32 v226, 16, v162
	v_and_b32_e32 v227, 0xffff0000, v162
	v_lshlrev_b32_e32 v228, 16, v163
	v_and_b32_e32 v229, 0xffff0000, v163
	v_lshlrev_b32_e32 v230, 16, v164
	v_and_b32_e32 v231, 0xffff0000, v164
	v_lshlrev_b32_e32 v232, 16, v165
	v_and_b32_e32 v233, 0xffff0000, v165
	v_mul_f32_e32 v110, v110, v226
	v_mul_f32_e32 v111, v111, v227
	v_mul_f32_e32 v112, v112, v228
	v_mul_f32_e32 v113, v113, v229
	v_mul_f32_e32 v106, v106, v230
	v_mul_f32_e32 v107, v107, v231
	v_mul_f32_e32 v108, v108, v232
	v_mul_f32_e32 v109, v109, v233
	s_waitcnt vmcnt(12)
	v_lshlrev_b32_e32 v226, 16, v174
	v_and_b32_e32 v227, 0xffff0000, v174
	v_lshlrev_b32_e32 v228, 16, v175
	v_and_b32_e32 v229, 0xffff0000, v175
	v_lshlrev_b32_e32 v230, 16, v176
	v_and_b32_e32 v231, 0xffff0000, v176
	v_lshlrev_b32_e32 v232, 16, v177
	v_and_b32_e32 v233, 0xffff0000, v177
	v_mul_f32_e32 v102, v102, v226
	v_mul_f32_e32 v103, v103, v227
	v_mul_f32_e32 v104, v104, v228
	v_mul_f32_e32 v105, v105, v229
	v_mul_f32_e32 v98, v98, v230
	v_mul_f32_e32 v99, v99, v231
	v_mul_f32_e32 v100, v100, v232
	v_mul_f32_e32 v101, v101, v233
	s_waitcnt vmcnt(11)
	v_lshlrev_b32_e32 v226, 16, v178
	v_and_b32_e32 v227, 0xffff0000, v178
	v_lshlrev_b32_e32 v228, 16, v179
	v_and_b32_e32 v229, 0xffff0000, v179
	v_lshlrev_b32_e32 v230, 16, v180
	v_and_b32_e32 v231, 0xffff0000, v180
	v_lshlrev_b32_e32 v232, 16, v181
	v_and_b32_e32 v233, 0xffff0000, v181
	v_mul_f32_e32 v94, v94, v226
	v_mul_f32_e32 v95, v95, v227
	v_mul_f32_e32 v96, v96, v228
	v_mul_f32_e32 v97, v97, v229
	v_mul_f32_e32 v90, v90, v230
	v_mul_f32_e32 v91, v91, v231
	v_mul_f32_e32 v92, v92, v232
	v_mul_f32_e32 v93, v93, v233
	s_waitcnt vmcnt(10)
	v_lshlrev_b32_e32 v226, 16, v182
	v_and_b32_e32 v227, 0xffff0000, v182
	v_lshlrev_b32_e32 v228, 16, v183
	v_and_b32_e32 v229, 0xffff0000, v183
	v_lshlrev_b32_e32 v230, 16, v184
	v_and_b32_e32 v231, 0xffff0000, v184
	v_lshlrev_b32_e32 v232, 16, v185
	v_and_b32_e32 v233, 0xffff0000, v185
	v_mul_f32_e32 v86, v86, v226
	v_mul_f32_e32 v87, v87, v227
	v_mul_f32_e32 v88, v88, v228
	v_mul_f32_e32 v89, v89, v229
	v_mul_f32_e32 v82, v82, v230
	v_mul_f32_e32 v83, v83, v231
	v_mul_f32_e32 v84, v84, v232
	v_mul_f32_e32 v85, v85, v233
	s_waitcnt vmcnt(9)
	v_lshlrev_b32_e32 v226, 16, v186
	v_and_b32_e32 v227, 0xffff0000, v186
	v_lshlrev_b32_e32 v228, 16, v187
	v_and_b32_e32 v229, 0xffff0000, v187
	v_lshlrev_b32_e32 v230, 16, v188
	v_and_b32_e32 v231, 0xffff0000, v188
	v_lshlrev_b32_e32 v232, 16, v189
	v_and_b32_e32 v233, 0xffff0000, v189
	v_mul_f32_e32 v78, v78, v226
	v_mul_f32_e32 v79, v79, v227
	v_mul_f32_e32 v80, v80, v228
	v_mul_f32_e32 v81, v81, v229
	v_mul_f32_e32 v74, v74, v230
	v_mul_f32_e32 v75, v75, v231
	v_mul_f32_e32 v76, v76, v232
	v_mul_f32_e32 v77, v77, v233
	s_waitcnt vmcnt(8)
; __device__ __forceinline__ float bflo(unsigned w) { return __uint_as_float(w << 16); }
; __device__ __forceinline__ float bfhi(unsigned w) { return __uint_as_float(w & 0xffff0000u); }
;     __device__ __forceinline__ void operator()(f32x4 (&acc)[2][2][4][2], const Unit& u, int wr, int wc, int fr, int fq) const {
;     ...
;                     const u32x4 gt = *(const u32x4*)(HM + row * HMW + C_AGATE + col);
;                     const f32x4 v0 = acc[ai][bj][m][0], v1 = acc[ai][bj][m][1];
;                     u32x4 w; w.x = pk2(v0[0] * bflo(gt.x), v0[1] * bfhi(gt.x)); w.y = pk2(v0[2] * bflo(gt.y), v0[3] * bfhi(gt.y));
;                     w.z = pk2(v1[0] * bflo(gt.z), v1[1] * bfhi(gt.z)); w.w = pk2(v1[2] * bflo(gt.w), v1[3] * bfhi(gt.w));
	v_lshlrev_b32_e32 v226, 16, v190
	v_and_b32_e32 v227, 0xffff0000, v190
	v_lshlrev_b32_e32 v228, 16, v191
	v_and_b32_e32 v229, 0xffff0000, v191
	v_lshlrev_b32_e32 v230, 16, v192
	v_and_b32_e32 v231, 0xffff0000, v192
	v_lshlrev_b32_e32 v232, 16, v193
	v_and_b32_e32 v233, 0xffff0000, v193
	v_mul_f32_e32 v70, v70, v226
	v_mul_f32_e32 v71, v71, v227
	v_mul_f32_e32 v72, v72, v228
	v_mul_f32_e32 v73, v73, v229
	v_mul_f32_e32 v66, v66, v230
	v_mul_f32_e32 v67, v67, v231
	v_mul_f32_e32 v68, v68, v232
	v_mul_f32_e32 v69, v69, v233
	s_waitcnt vmcnt(7)
	v_lshlrev_b32_e32 v226, 16, v194
	v_and_b32_e32 v227, 0xffff0000, v194
	v_lshlrev_b32_e32 v228, 16, v195
	v_and_b32_e32 v229, 0xffff0000, v195
	v_lshlrev_b32_e32 v230, 16, v196
	v_and_b32_e32 v231, 0xffff0000, v196
	v_lshlrev_b32_e32 v232, 16, v197
	v_and_b32_e32 v233, 0xffff0000, v197
	v_mul_f32_e32 v62, v62, v226
	v_mul_f32_e32 v63, v63, v227
	v_mul_f32_e32 v64, v64, v228
	v_mul_f32_e32 v65, v65, v229
	v_mul_f32_e32 v58, v58, v230
	v_mul_f32_e32 v59, v59, v231
	v_mul_f32_e32 v60, v60, v232
	v_mul_f32_e32 v61, v61, v233
	s_waitcnt vmcnt(6)
	v_lshlrev_b32_e32 v226, 16, v198
	v_and_b32_e32 v227, 0xffff0000, v198
	v_lshlrev_b32_e32 v228, 16, v199
	v_and_b32_e32 v229, 0xffff0000, v199
	v_lshlrev_b32_e32 v230, 16, v200
	v_and_b32_e32 v231, 0xffff0000, v200
	v_lshlrev_b32_e32 v232, 16, v201
	v_and_b32_e32 v233, 0xffff0000, v201
	v_mul_f32_e32 v54, v54, v226
	v_mul_f32_e32 v55, v55, v227
	v_mul_f32_e32 v56, v56, v228
	v_mul_f32_e32 v57, v57, v229
	v_mul_f32_e32 v50, v50, v230
	v_mul_f32_e32 v51, v51, v231
	v_mul_f32_e32 v52, v52, v232
	v_mul_f32_e32 v53, v53, v233
	s_waitcnt vmcnt(5)
	v_lshlrev_b32_e32 v226, 16, v202
	v_and_b32_e32 v227, 0xffff0000, v202
	v_lshlrev_b32_e32 v228, 16, v203
	v_and_b32_e32 v229, 0xffff0000, v203
	v_lshlrev_b32_e32 v230, 16, v204
	v_and_b32_e32 v231, 0xffff0000, v204
	v_lshlrev_b32_e32 v232, 16, v205
	v_and_b32_e32 v233, 0xffff0000, v205
	v_mul_f32_e32 v46, v46, v226
	v_mul_f32_e32 v47, v47, v227
	v_mul_f32_e32 v48, v48, v228
	v_mul_f32_e32 v49, v49, v229
	v_mul_f32_e32 v42, v42, v230
	v_mul_f32_e32 v43, v43, v231
	v_mul_f32_e32 v44, v44, v232
	v_mul_f32_e32 v45, v45, v233
	s_waitcnt vmcnt(4)
	v_lshlrev_b32_e32 v226, 16, v206
	v_and_b32_e32 v227, 0xffff0000, v206
	v_lshlrev_b32_e32 v228, 16, v207
	v_and_b32_e32 v229, 0xffff0000, v207
	v_lshlrev_b32_e32 v230, 16, v208
	v_and_b32_e32 v231, 0xffff0000, v208
	v_lshlrev_b32_e32 v232, 16, v209
	v_and_b32_e32 v233, 0xffff0000, v209
	v_mul_f32_e32 v38, v38, v226
	v_mul_f32_e32 v39, v39, v227
	v_mul_f32_e32 v40, v40, v228
	v_mul_f32_e32 v41, v41, v229
	v_mul_f32_e32 v34, v34, v230
	v_mul_f32_e32 v35, v35, v231
	v_mul_f32_e32 v36, v36, v232
	v_mul_f32_e32 v37, v37, v233
	s_waitcnt vmcnt(3)
	v_lshlrev_b32_e32 v226, 16, v210
	v_and_b32_e32 v227, 0xffff0000, v210
	v_lshlrev_b32_e32 v228, 16, v211
	v_and_b32_e32 v229, 0xffff0000, v211
	v_lshlrev_b32_e32 v230, 16, v212
	v_and_b32_e32 v231, 0xffff0000, v212
	v_lshlrev_b32_e32 v232, 16, v213
	v_and_b32_e32 v233, 0xffff0000, v213
	v_mul_f32_e32 v30, v30, v226
	v_mul_f32_e32 v31, v31, v227
	v_mul_f32_e32 v32, v32, v228
	v_mul_f32_e32 v33, v33, v229
	v_mul_f32_e32 v26, v26, v230
	v_mul_f32_e32 v27, v27, v231
	v_mul_f32_e32 v28, v28, v232
	v_mul_f32_e32 v29, v29, v233
	s_waitcnt vmcnt(2)
	v_lshlrev_b32_e32 v226, 16, v214
	v_and_b32_e32 v227, 0xffff0000, v214
	v_lshlrev_b32_e32 v228, 16, v215
	v_and_b32_e32 v229, 0xffff0000, v215
	v_lshlrev_b32_e32 v230, 16, v216
	v_and_b32_e32 v231, 0xffff0000, v216
	v_lshlrev_b32_e32 v232, 16, v217
	v_and_b32_e32 v233, 0xffff0000, v217
	v_mul_f32_e32 v22, v22, v226
	v_mul_f32_e32 v23, v23, v227
	v_mul_f32_e32 v24, v24, v228
	v_mul_f32_e32 v25, v25, v229
	v_mul_f32_e32 v18, v18, v230
	v_mul_f32_e32 v19, v19, v231
	v_mul_f32_e32 v20, v20, v232
	v_mul_f32_e32 v21, v21, v233
	s_waitcnt vmcnt(1)
	v_lshlrev_b32_e32 v226, 16, v218
	v_and_b32_e32 v227, 0xffff0000, v218
	v_lshlrev_b32_e32 v228, 16, v219
	v_and_b32_e32 v229, 0xffff0000, v219
	v_lshlrev_b32_e32 v230, 16, v220
	v_and_b32_e32 v231, 0xffff0000, v220
	v_lshlrev_b32_e32 v232, 16, v221
	v_and_b32_e32 v233, 0xffff0000, v221
	v_mul_f32_e32 v14, v14, v226
	v_mul_f32_e32 v15, v15, v227
	v_mul_f32_e32 v16, v16, v228
	v_mul_f32_e32 v17, v17, v229
	v_mul_f32_e32 v10, v10, v230
	v_mul_f32_e32 v11, v11, v231
	v_mul_f32_e32 v12, v12, v232
	v_mul_f32_e32 v13, v13, v233
	s_waitcnt vmcnt(0)
; __device__ __forceinline__ float bflo(unsigned w) { return __uint_as_float(w << 16); }
; __device__ __forceinline__ float bfhi(unsigned w) { return __uint_as_float(w & 0xffff0000u); }
;     __device__ __forceinline__ void operator()(f32x4 (&acc)[2][2][4][2], const Unit& u, int wr, int wc, int fr, int fq) const {
;     ...
;                     u32x4 w; w.x = pk2(v0[0] * bflo(gt.x), v0[1] * bfhi(gt.x)); w.y = pk2(v0[2] * bflo(gt.y), v0[3] * bfhi(gt.y));
;                     w.z = pk2(v1[0] * bflo(gt.z), v1[1] * bfhi(gt.z)); w.w = pk2(v1[2] * bflo(gt.w), v1[3] * bfhi(gt.w));
;                     *(u32x4*)(YA + row * 1024 + col) = w; } }
	v_lshlrev_b32_e32 v226, 16, v222
	v_and_b32_e32 v227, 0xffff0000, v222
	v_lshlrev_b32_e32 v228, 16, v223
	v_and_b32_e32 v229, 0xffff0000, v223
	v_lshlrev_b32_e32 v230, 16, v224
	v_and_b32_e32 v231, 0xffff0000, v224
	v_lshlrev_b32_e32 v232, 16, v225
	v_and_b32_e32 v233, 0xffff0000, v225
	v_mul_f32_e32 v6, v6, v226
	v_mul_f32_e32 v7, v7, v227
	v_mul_f32_e32 v8, v8, v228
	v_mul_f32_e32 v9, v9, v229
	v_mul_f32_e32 v2, v2, v230
	v_mul_f32_e32 v3, v3, v231
	v_mul_f32_e32 v4, v4, v232
	v_mul_f32_e32 v5, v5, v233
	v_lshl_add_u32 v234, v152, 11, v153
	v_cvt_pk_bf16_f32 v148, v126, v127
	v_cvt_pk_bf16_f32 v149, v128, v129
	v_cvt_pk_bf16_f32 v150, v122, v123
	v_cvt_pk_bf16_f32 v151, v124, v125
	global_store_dwordx4 v234, v[148:151], s[38:39]
	v_cvt_pk_bf16_f32 v158, v118, v119
	v_cvt_pk_bf16_f32 v159, v120, v121
	v_cvt_pk_bf16_f32 v160, v114, v115
	v_cvt_pk_bf16_f32 v161, v116, v117
	global_store_dwordx4 v234, v[158:161], s[38:39] offset:256
	v_add_u32_e32 v235, 0x8000, v234
	v_cvt_pk_bf16_f32 v162, v110, v111
	v_cvt_pk_bf16_f32 v163, v112, v113
	v_cvt_pk_bf16_f32 v164, v106, v107
	v_cvt_pk_bf16_f32 v165, v108, v109
	global_store_dwordx4 v235, v[162:165], s[38:39]
	v_cvt_pk_bf16_f32 v174, v102, v103
	v_cvt_pk_bf16_f32 v175, v104, v105
	v_cvt_pk_bf16_f32 v176, v98, v99
	v_cvt_pk_bf16_f32 v177, v100, v101
	global_store_dwordx4 v235, v[174:177], s[38:39] offset:256
	v_add_u32_e32 v235, 0x10000, v234
	v_cvt_pk_bf16_f32 v178, v94, v95
	v_cvt_pk_bf16_f32 v179, v96, v97
	v_cvt_pk_bf16_f32 v180, v90, v91
	v_cvt_pk_bf16_f32 v181, v92, v93
	global_store_dwordx4 v235, v[178:181], s[38:39]
	v_cvt_pk_bf16_f32 v182, v86, v87
	v_cvt_pk_bf16_f32 v183, v88, v89
	v_cvt_pk_bf16_f32 v184, v82, v83
	v_cvt_pk_bf16_f32 v185, v84, v85
	global_store_dwordx4 v235, v[182:185], s[38:39] offset:256
	v_add_u32_e32 v235, 0x18000, v234
	v_cvt_pk_bf16_f32 v186, v78, v79
	v_cvt_pk_bf16_f32 v187, v80, v81
	v_cvt_pk_bf16_f32 v188, v74, v75
	v_cvt_pk_bf16_f32 v189, v76, v77
	global_store_dwordx4 v235, v[186:189], s[38:39]
	v_cvt_pk_bf16_f32 v190, v70, v71
	v_cvt_pk_bf16_f32 v191, v72, v73
	v_cvt_pk_bf16_f32 v192, v66, v67
	v_cvt_pk_bf16_f32 v193, v68, v69
	global_store_dwordx4 v235, v[190:193], s[38:39] offset:256
	v_add_u32_e32 v235, 0x40000, v234
	v_cvt_pk_bf16_f32 v194, v62, v63
	v_cvt_pk_bf16_f32 v195, v64, v65
	v_cvt_pk_bf16_f32 v196, v58, v59
	v_cvt_pk_bf16_f32 v197, v60, v61
	global_store_dwordx4 v235, v[194:197], s[38:39]
	v_cvt_pk_bf16_f32 v198, v54, v55
	v_cvt_pk_bf16_f32 v199, v56, v57
	v_cvt_pk_bf16_f32 v200, v50, v51
	v_cvt_pk_bf16_f32 v201, v52, v53
	global_store_dwordx4 v235, v[198:201], s[38:39] offset:256
	v_add_u32_e32 v235, 0x48000, v234
	v_cvt_pk_bf16_f32 v202, v46, v47
	v_cvt_pk_bf16_f32 v203, v48, v49
	v_cvt_pk_bf16_f32 v204, v42, v43
	v_cvt_pk_bf16_f32 v205, v44, v45
	global_store_dwordx4 v235, v[202:205], s[38:39]
	v_cvt_pk_bf16_f32 v206, v38, v39
	v_cvt_pk_bf16_f32 v207, v40, v41
	v_cvt_pk_bf16_f32 v208, v34, v35
	v_cvt_pk_bf16_f32 v209, v36, v37
	global_store_dwordx4 v235, v[206:209], s[38:39] offset:256
	v_add_u32_e32 v235, 0x50000, v234
	v_cvt_pk_bf16_f32 v210, v30, v31
	v_cvt_pk_bf16_f32 v211, v32, v33
	v_cvt_pk_bf16_f32 v212, v26, v27
	v_cvt_pk_bf16_f32 v213, v28, v29
	global_store_dwordx4 v235, v[210:213], s[38:39]
	v_cvt_pk_bf16_f32 v214, v22, v23
	v_cvt_pk_bf16_f32 v215, v24, v25
	v_cvt_pk_bf16_f32 v216, v18, v19
	v_cvt_pk_bf16_f32 v217, v20, v21
	global_store_dwordx4 v235, v[214:217], s[38:39] offset:256
	v_add_u32_e32 v235, 0x58000, v234
	v_cvt_pk_bf16_f32 v218, v14, v15
	v_cvt_pk_bf16_f32 v219, v16, v17
	v_cvt_pk_bf16_f32 v220, v10, v11
	v_cvt_pk_bf16_f32 v221, v12, v13
	global_store_dwordx4 v235, v[218:221], s[38:39]
	v_cvt_pk_bf16_f32 v222, v6, v7
	v_cvt_pk_bf16_f32 v223, v8, v9
	v_cvt_pk_bf16_f32 v224, v2, v3
	v_cvt_pk_bf16_f32 v225, v4, v5
	global_store_dwordx4 v235, v[222:225], s[38:39] offset:256
	s_and_b64 vcc, exec, s[40:41]
	s_cbranch_vccnz .LBB0_612
	s_andn2_b64 vcc, exec, s[34:35]
	s_cbranch_vccnz .LBB0_611
	s_barrier
	s_branch .LBB0_611
